# in-proj A / INB phase start: early vmcnt(0) in the q/k-gain staging removed (disjoint lanes), the gain loads overlap the first K-tile DMAs; on top of v86
# speedup vs baseline: 1.0037x; 1.0037x over previous
; #define PG8_LAS __attribute__((address_space(3)))
; #define PG8_STAGE(bufoff, gbase, voff) do { _Pragma("unroll") for (int _i = 0; _i < 2; ++_i) \
;         __builtin_amdgcn_global_load_lds((const unsigned*)((const char*)(gbase) + (voff)[_i]), (PG8_LAS unsigned*)(lds + (bufoff) + ldsw + _i * 8192), 16, 0, 0); } while (0)
;     __device__ __forceinline__ void stage_consts(PG8_LAS float* gl, int tid) const { if (tid < 2 * NGQ) gl[tid] = (tid < NGQ) ? qg[tid] * qscale : kg[tid - NGQ]; }
;     ...
;     PG8_STAGE(PG8_SB(0, 0), cB, voffB); PG8_STAGE(PG8_SB(0, 1), cB + hstepB, voffB); PG8_STAGE(PG8_SA(0, 0), cA, voffA); PG8_STAGE(PG8_SA(0, 1), cA + hstep, voffA);
;     E.stage_consts((PG8_LAS float*)(lds + 131072) + 1024, tid);
.LBB0_195:
	s_andn2_saveexec_b64 s[24:25], s[24:25]
	s_cbranch_execz .LBB0_197
	s_nop 1
	v_lshl_add_u64 v[2:3], v[0:1], 2, s[52:53]
	global_load_dword v1, v[2:3], off
	s_waitcnt vmcnt(0)
	v_mul_f32_e32 v2, 0x3e38aa3b, v1

; #define PG8_LAS __attribute__((address_space(3)))
;     __device__ __forceinline__ void stage_consts(PG8_LAS float* gl, int tid) const { if (tid < 2 * NGQ) gl[tid] = (tid < NGQ) ? qg[tid] * qscale : kg[tid - NGQ]; }
; __global__ void __launch_bounds__(NWAVES * 64, 2) fwd_kernel(Args args) {
;     ...
;             pg8::Gemm g{(const bf16*)(ws + WS_X1B) + (size_t)cb * MCHB * DM, (const bf16*)(ws + WS_WBIN), MCHB, NB_IN, DM};
;             pg8::StaticOrder S; S.init(MCHB, NB_IN, F.G, (int)blockIdx.x);
;             pg8::EpiIn<1> E{nullptr, nullptr, 0, 1, (bf16*)(ws + WS_QKVB), SECB, (bf16*)(ws + WS_GATEB), part2, args.in[9], args.in[10], cb * MCHB, QSCALE};
;             pg8::gemm_phase<pg8::EpiIn<1>, pg8::StaticOrder, true>(F.lds + RING_OFF, g, S, E, F.wave);
.LBB0_517:
	s_andn2_saveexec_b64 s[10:11], s[10:11]
	s_cbranch_execz .LBB0_519
	v_readlane_b32 s48, v253, 6
	v_readlane_b32 s50, v253, 8
	v_readlane_b32 s51, v253, 9
	v_readlane_b32 s49, v253, 7
	v_readlane_b32 s52, v253, 10
	s_nop 1
	v_lshl_add_u64 v[114:115], v[112:113], 2, s[50:51]
	global_load_dword v113, v[114:115], off
	v_readlane_b32 s53, v253, 11
	v_readlane_b32 s54, v253, 12
	v_readlane_b32 s55, v253, 13
	s_waitcnt vmcnt(0)
	v_mul_f32_e32 v114, 0x3e38aa3b, v113
